# P5 work-queue weight conversion chunks: hand-written LDS-free transposer (dwordx4 row-segment loads, in-lane bf16 packing, full-line stores, 3 items in flight)
# baseline (speedup 1.0000x reference)
.LBB0_984:
	s_and_b64 vcc, exec, s[66:67]
	s_cbranch_vccz .LBB0_1059
	s_add_i32 s96, s89, s41
	s_movk_i32 s20, 0x588
	s_movk_i32 s44, 0x120
	s_mov_b32 s76, 0x20700000
	s_movk_i32 s77, 0x100
	s_movk_i32 s78, 0x1000
	s_cmpk_lt_u32 s96, 0x588
	s_cselect_b32 s20, 0x548, s20
	s_cselect_b32 s44, 0xc0, s44
	s_cselect_b32 s76, 0x1f700000, s76
	s_cselect_b32 s77, 0x800, s77
	s_cselect_b32 s78, 0x1000, s78
	s_cmpk_lt_u32 s96, 0x548
	s_cselect_b32 s20, 0x508, s20
	s_cselect_b32 s44, 0x60, s44
	s_cselect_b32 s76, 0x1e700000, s76
	s_cselect_b32 s77, 0x800, s77
	s_cselect_b32 s78, 0x1000, s78
	s_cmpk_lt_u32 s96, 0x508
	s_cselect_b32 s20, 0x488, s20
	s_cselect_b32 s44, 0x118, s44
	s_cselect_b32 s76, 0x1c700000, s76
	s_cselect_b32 s77, 0x1000, s77
	s_cselect_b32 s78, 0x1000, s78
	s_cmpk_lt_u32 s96, 0x488
	s_cselect_b32 s20, 0x408, s20
	s_cselect_b32 s44, 0xc8, s44
	s_cselect_b32 s76, 0x1a700000, s76
	s_cselect_b32 s77, 0x1000, s77
	s_cselect_b32 s78, 0x1000, s78
	s_cmpk_lt_u32 s96, 0x408
	s_cselect_b32 s20, 0x2b0, s20
	s_cselect_b32 s44, 0x108, s44
	s_cselect_b32 s76, 0x15100000, s76
	s_cselect_b32 s77, 0x2b00, s77
	s_cselect_b32 s78, 0x1000, s78
	s_cmpk_lt_u32 s96, 0x2b0
	s_cselect_b32 s20, 0x0, s20
	s_cselect_b32 s44, 0xf0, s44
	s_cselect_b32 s76, 0xa500000, s76
	s_cselect_b32 s77, 0x1000, s77
	s_cselect_b32 s78, 0x5600, s78
	s_load_dwordx2 s[36:37], s[0:1], s44
	s_sub_i32 s79, s96, s20
	s_lshl_b32 s79, s79, 6
	s_lshl_b32 s95, s90, 3
	s_add_i32 s79, s79, s95
	s_mul_i32 s93, s79, 0xbe84
	s_lshr_b32 s93, s93, 25
	s_mul_i32 s94, s93, 0x2b0
	s_sub_i32 s94, s79, s94
	s_lshr_b32 s95, s79, 7
	s_and_b32 s74, s79, 0x7f
	s_cmpk_lt_u32 s96, 0x2b0
	s_cselect_b32 s93, s93, s95
	s_cselect_b32 s94, s94, s74
	s_lshl_b32 s93, s93, 6
	s_lshl_b32 s94, s94, 5
	s_mul_i32 s95, s93, s78
	s_add_i32 s95, s95, s94
	s_lshl_b32 s95, s95, 2
	s_lshl_b32 s66, s78, 2
	s_mov_b32 s67, 0
	s_lshl_b32 s68, s77, 1
	s_mov_b32 s69, 0
	s_lshl_b32 s70, s77, 2
	s_mov_b32 s71, 0
	s_mul_i32 s72, s77, 6
	s_mov_b32 s73, 0
	s_add_u32 s38, s30, s76
	s_addc_u32 s39, s31, 0
	s_lshl_b32 s79, s93, 1
	v_lshrrev_b32_e32 v230, 3, v162
	v_lshl_add_u32 v230, v230, 2, s94
	v_mul_lo_u32 v230, v230, s68
	v_and_b32_e32 v231, 7, v162
	v_lshl_add_u32 v230, v231, 4, v230
	v_add_u32_e32 v230, s79, v230
	v_mov_b32_e32 v231, 0
	v_lshl_add_u64 v[92:93], s[38:39], 0, v[230:231]
	v_and_b32_e32 v230, 7, v162
	s_lshl_b32 s79, s78, 5
	v_mul_lo_u32 v230, v230, s79
	v_lshrrev_b32_e32 v2, 3, v162
	v_lshl_add_u32 v230, v2, 4, v230
	s_waitcnt lgkmcnt(0)
	s_add_u32 s36, s36, s95
	s_addc_u32 s37, s37, 0
	v_lshl_add_u64 v[240:241], s[36:37], 0, v[230:231]
	s_lshl_b32 s74, s77, 6
	s_mov_b32 s75, 0
	v_mov_b64_e32 v[2:3], v[240:241]
	global_load_dwordx4 v[4:7], v[2:3], off nt
	v_lshl_add_u64 v[2:3], v[2:3], 0, s[66:67]
	global_load_dwordx4 v[8:11], v[2:3], off nt
	v_lshl_add_u64 v[2:3], v[2:3], 0, s[66:67]
	global_load_dwordx4 v[12:15], v[2:3], off nt
	v_lshl_add_u64 v[2:3], v[2:3], 0, s[66:67]
	global_load_dwordx4 v[16:19], v[2:3], off nt
	v_lshl_add_u64 v[2:3], v[2:3], 0, s[66:67]
	global_load_dwordx4 v[20:23], v[2:3], off nt
	v_lshl_add_u64 v[2:3], v[2:3], 0, s[66:67]
	global_load_dwordx4 v[24:27], v[2:3], off nt
	v_lshl_add_u64 v[2:3], v[2:3], 0, s[66:67]
	global_load_dwordx4 v[28:31], v[2:3], off nt
	v_lshl_add_u64 v[2:3], v[2:3], 0, s[66:67]
	global_load_dwordx4 v[32:35], v[2:3], off nt
	v_mov_b64_e32 v[2:3], v[240:241]
	global_load_dwordx4 v[36:39], v[2:3], off offset:128 nt
	v_lshl_add_u64 v[2:3], v[2:3], 0, s[66:67]
	global_load_dwordx4 v[40:43], v[2:3], off offset:128 nt
	v_lshl_add_u64 v[2:3], v[2:3], 0, s[66:67]
	global_load_dwordx4 v[44:47], v[2:3], off offset:128 nt
	v_lshl_add_u64 v[2:3], v[2:3], 0, s[66:67]
	global_load_dwordx4 v[48:51], v[2:3], off offset:128 nt
	v_lshl_add_u64 v[2:3], v[2:3], 0, s[66:67]
	global_load_dwordx4 v[52:55], v[2:3], off offset:128 nt
	v_lshl_add_u64 v[2:3], v[2:3], 0, s[66:67]
	global_load_dwordx4 v[56:59], v[2:3], off offset:128 nt
	v_lshl_add_u64 v[2:3], v[2:3], 0, s[66:67]
	global_load_dwordx4 v[60:63], v[2:3], off offset:128 nt
	v_lshl_add_u64 v[2:3], v[2:3], 0, s[66:67]
	global_load_dwordx4 v[64:67], v[2:3], off offset:128 nt
	v_mov_b64_e32 v[2:3], v[240:241]
	global_load_dwordx4 v[68:71], v[2:3], off offset:256 nt
	v_lshl_add_u64 v[2:3], v[2:3], 0, s[66:67]
	global_load_dwordx4 v[72:75], v[2:3], off offset:256 nt
	v_lshl_add_u64 v[2:3], v[2:3], 0, s[66:67]
	global_load_dwordx4 v[76:79], v[2:3], off offset:256 nt
	v_lshl_add_u64 v[2:3], v[2:3], 0, s[66:67]
	global_load_dwordx4 v[80:83], v[2:3], off offset:256 nt
	v_lshl_add_u64 v[2:3], v[2:3], 0, s[66:67]
	global_load_dwordx4 v[84:87], v[2:3], off offset:256 nt
	v_lshl_add_u64 v[2:3], v[2:3], 0, s[66:67]
	global_load_dwordx4 v[88:91], v[2:3], off offset:256 nt
	v_lshl_add_u64 v[2:3], v[2:3], 0, s[66:67]
	global_load_dwordx4 v[232:235], v[2:3], off offset:256 nt
	v_lshl_add_u64 v[2:3], v[2:3], 0, s[66:67]
	global_load_dwordx4 v[236:239], v[2:3], off offset:256 nt
	s_waitcnt vmcnt(16)
	v_cvt_pk_bf16_f32 v244, v4, v8
	v_cvt_pk_bf16_f32 v245, v12, v16
	v_cvt_pk_bf16_f32 v246, v20, v24
	v_cvt_pk_bf16_f32 v247, v28, v32
	v_cvt_pk_bf16_f32 v248, v5, v9
	v_cvt_pk_bf16_f32 v249, v13, v17
	v_cvt_pk_bf16_f32 v250, v21, v25
	v_cvt_pk_bf16_f32 v251, v29, v33
	global_store_dwordx4 v[92:93], v[244:247], off
	v_lshl_add_u64 v[230:231], v[92:93], 0, s[68:69]
	global_store_dwordx4 v[230:231], v[248:251], off
	s_nop 1
	v_cvt_pk_bf16_f32 v244, v6, v10
	v_cvt_pk_bf16_f32 v245, v14, v18
	v_cvt_pk_bf16_f32 v246, v22, v26
	v_cvt_pk_bf16_f32 v247, v30, v34
	v_cvt_pk_bf16_f32 v248, v7, v11
	v_cvt_pk_bf16_f32 v249, v15, v19
	v_cvt_pk_bf16_f32 v250, v23, v27
	v_cvt_pk_bf16_f32 v251, v31, v35
	v_lshl_add_u64 v[230:231], v[92:93], 0, s[70:71]
	global_store_dwordx4 v[230:231], v[244:247], off
	v_lshl_add_u64 v[230:231], v[92:93], 0, s[72:73]
	global_store_dwordx4 v[230:231], v[248:251], off
	v_lshl_add_u64 v[92:93], v[92:93], 0, s[74:75]
	v_mov_b64_e32 v[2:3], v[240:241]
	global_load_dwordx4 v[4:7], v[2:3], off offset:384 nt
	v_lshl_add_u64 v[2:3], v[2:3], 0, s[66:67]
	global_load_dwordx4 v[8:11], v[2:3], off offset:384 nt
	v_lshl_add_u64 v[2:3], v[2:3], 0, s[66:67]
	global_load_dwordx4 v[12:15], v[2:3], off offset:384 nt
	v_lshl_add_u64 v[2:3], v[2:3], 0, s[66:67]
	global_load_dwordx4 v[16:19], v[2:3], off offset:384 nt
	v_lshl_add_u64 v[2:3], v[2:3], 0, s[66:67]
	global_load_dwordx4 v[20:23], v[2:3], off offset:384 nt
	v_lshl_add_u64 v[2:3], v[2:3], 0, s[66:67]
	global_load_dwordx4 v[24:27], v[2:3], off offset:384 nt
	v_lshl_add_u64 v[2:3], v[2:3], 0, s[66:67]
	global_load_dwordx4 v[28:31], v[2:3], off offset:384 nt
	v_lshl_add_u64 v[2:3], v[2:3], 0, s[66:67]
	global_load_dwordx4 v[32:35], v[2:3], off offset:384 nt
	s_waitcnt vmcnt(20)
	v_cvt_pk_bf16_f32 v244, v36, v40
	v_cvt_pk_bf16_f32 v245, v44, v48
	v_cvt_pk_bf16_f32 v246, v52, v56
	v_cvt_pk_bf16_f32 v247, v60, v64
	v_cvt_pk_bf16_f32 v248, v37, v41
	v_cvt_pk_bf16_f32 v249, v45, v49
	v_cvt_pk_bf16_f32 v250, v53, v57
	v_cvt_pk_bf16_f32 v251, v61, v65
	global_store_dwordx4 v[92:93], v[244:247], off
	v_lshl_add_u64 v[230:231], v[92:93], 0, s[68:69]
	global_store_dwordx4 v[230:231], v[248:251], off
	s_nop 1
	v_cvt_pk_bf16_f32 v244, v38, v42
	v_cvt_pk_bf16_f32 v245, v46, v50
	v_cvt_pk_bf16_f32 v246, v54, v58
	v_cvt_pk_bf16_f32 v247, v62, v66
	v_cvt_pk_bf16_f32 v248, v39, v43
	v_cvt_pk_bf16_f32 v249, v47, v51
	v_cvt_pk_bf16_f32 v250, v55, v59
	v_cvt_pk_bf16_f32 v251, v63, v67
	v_lshl_add_u64 v[230:231], v[92:93], 0, s[70:71]
	global_store_dwordx4 v[230:231], v[244:247], off
	v_lshl_add_u64 v[230:231], v[92:93], 0, s[72:73]
	global_store_dwordx4 v[230:231], v[248:251], off
	v_lshl_add_u64 v[92:93], v[92:93], 0, s[74:75]
	v_mov_b64_e32 v[2:3], v[240:241]
	global_load_dwordx4 v[36:39], v[2:3], off offset:512 nt
	v_lshl_add_u64 v[2:3], v[2:3], 0, s[66:67]
	global_load_dwordx4 v[40:43], v[2:3], off offset:512 nt
	v_lshl_add_u64 v[2:3], v[2:3], 0, s[66:67]
	global_load_dwordx4 v[44:47], v[2:3], off offset:512 nt
	v_lshl_add_u64 v[2:3], v[2:3], 0, s[66:67]
	global_load_dwordx4 v[48:51], v[2:3], off offset:512 nt
	v_lshl_add_u64 v[2:3], v[2:3], 0, s[66:67]
	global_load_dwordx4 v[52:55], v[2:3], off offset:512 nt
	v_lshl_add_u64 v[2:3], v[2:3], 0, s[66:67]
	global_load_dwordx4 v[56:59], v[2:3], off offset:512 nt
	v_lshl_add_u64 v[2:3], v[2:3], 0, s[66:67]
	global_load_dwordx4 v[60:63], v[2:3], off offset:512 nt
	v_lshl_add_u64 v[2:3], v[2:3], 0, s[66:67]
	global_load_dwordx4 v[64:67], v[2:3], off offset:512 nt
	s_waitcnt vmcnt(24)
	v_cvt_pk_bf16_f32 v244, v68, v72
	v_cvt_pk_bf16_f32 v245, v76, v80
	v_cvt_pk_bf16_f32 v246, v84, v88
	v_cvt_pk_bf16_f32 v247, v232, v236
	v_cvt_pk_bf16_f32 v248, v69, v73
	v_cvt_pk_bf16_f32 v249, v77, v81
	v_cvt_pk_bf16_f32 v250, v85, v89
	v_cvt_pk_bf16_f32 v251, v233, v237
	global_store_dwordx4 v[92:93], v[244:247], off
	v_lshl_add_u64 v[230:231], v[92:93], 0, s[68:69]
	global_store_dwordx4 v[230:231], v[248:251], off
	s_nop 1
	v_cvt_pk_bf16_f32 v244, v70, v74
	v_cvt_pk_bf16_f32 v245, v78, v82
	v_cvt_pk_bf16_f32 v246, v86, v90
	v_cvt_pk_bf16_f32 v247, v234, v238
	v_cvt_pk_bf16_f32 v248, v71, v75
	v_cvt_pk_bf16_f32 v249, v79, v83
	v_cvt_pk_bf16_f32 v250, v87, v91
	v_cvt_pk_bf16_f32 v251, v235, v239
	v_lshl_add_u64 v[230:231], v[92:93], 0, s[70:71]
	global_store_dwordx4 v[230:231], v[244:247], off
	v_lshl_add_u64 v[230:231], v[92:93], 0, s[72:73]
	global_store_dwordx4 v[230:231], v[248:251], off
	v_lshl_add_u64 v[92:93], v[92:93], 0, s[74:75]
	v_mov_b64_e32 v[2:3], v[240:241]
	global_load_dwordx4 v[68:71], v[2:3], off offset:640 nt
	v_lshl_add_u64 v[2:3], v[2:3], 0, s[66:67]
	global_load_dwordx4 v[72:75], v[2:3], off offset:640 nt
	v_lshl_add_u64 v[2:3], v[2:3], 0, s[66:67]
	global_load_dwordx4 v[76:79], v[2:3], off offset:640 nt
	v_lshl_add_u64 v[2:3], v[2:3], 0, s[66:67]
	global_load_dwordx4 v[80:83], v[2:3], off offset:640 nt
	v_lshl_add_u64 v[2:3], v[2:3], 0, s[66:67]
	global_load_dwordx4 v[84:87], v[2:3], off offset:640 nt
	v_lshl_add_u64 v[2:3], v[2:3], 0, s[66:67]
	global_load_dwordx4 v[88:91], v[2:3], off offset:640 nt
	v_lshl_add_u64 v[2:3], v[2:3], 0, s[66:67]
	global_load_dwordx4 v[232:235], v[2:3], off offset:640 nt
	v_lshl_add_u64 v[2:3], v[2:3], 0, s[66:67]
	global_load_dwordx4 v[236:239], v[2:3], off offset:640 nt
	s_waitcnt vmcnt(24)
	v_cvt_pk_bf16_f32 v244, v4, v8
	v_cvt_pk_bf16_f32 v245, v12, v16
	v_cvt_pk_bf16_f32 v246, v20, v24
	v_cvt_pk_bf16_f32 v247, v28, v32
	v_cvt_pk_bf16_f32 v248, v5, v9
	v_cvt_pk_bf16_f32 v249, v13, v17
	v_cvt_pk_bf16_f32 v250, v21, v25
	v_cvt_pk_bf16_f32 v251, v29, v33
	global_store_dwordx4 v[92:93], v[244:247], off
	v_lshl_add_u64 v[230:231], v[92:93], 0, s[68:69]
	global_store_dwordx4 v[230:231], v[248:251], off
	s_nop 1
	v_cvt_pk_bf16_f32 v244, v6, v10
	v_cvt_pk_bf16_f32 v245, v14, v18
	v_cvt_pk_bf16_f32 v246, v22, v26
	v_cvt_pk_bf16_f32 v247, v30, v34
	v_cvt_pk_bf16_f32 v248, v7, v11
	v_cvt_pk_bf16_f32 v249, v15, v19
	v_cvt_pk_bf16_f32 v250, v23, v27
	v_cvt_pk_bf16_f32 v251, v31, v35
	v_lshl_add_u64 v[230:231], v[92:93], 0, s[70:71]
	global_store_dwordx4 v[230:231], v[244:247], off
	v_lshl_add_u64 v[230:231], v[92:93], 0, s[72:73]
	global_store_dwordx4 v[230:231], v[248:251], off
	v_lshl_add_u64 v[92:93], v[92:93], 0, s[74:75]
	v_mov_b64_e32 v[2:3], v[240:241]
	global_load_dwordx4 v[4:7], v[2:3], off offset:768 nt
	v_lshl_add_u64 v[2:3], v[2:3], 0, s[66:67]
	global_load_dwordx4 v[8:11], v[2:3], off offset:768 nt
	v_lshl_add_u64 v[2:3], v[2:3], 0, s[66:67]
	global_load_dwordx4 v[12:15], v[2:3], off offset:768 nt
	v_lshl_add_u64 v[2:3], v[2:3], 0, s[66:67]
	global_load_dwordx4 v[16:19], v[2:3], off offset:768 nt
	v_lshl_add_u64 v[2:3], v[2:3], 0, s[66:67]
	global_load_dwordx4 v[20:23], v[2:3], off offset:768 nt
	v_lshl_add_u64 v[2:3], v[2:3], 0, s[66:67]
	global_load_dwordx4 v[24:27], v[2:3], off offset:768 nt
	v_lshl_add_u64 v[2:3], v[2:3], 0, s[66:67]
	global_load_dwordx4 v[28:31], v[2:3], off offset:768 nt
	v_lshl_add_u64 v[2:3], v[2:3], 0, s[66:67]
	global_load_dwordx4 v[32:35], v[2:3], off offset:768 nt
	s_waitcnt vmcnt(24)
	v_cvt_pk_bf16_f32 v244, v36, v40
	v_cvt_pk_bf16_f32 v245, v44, v48
	v_cvt_pk_bf16_f32 v246, v52, v56
	v_cvt_pk_bf16_f32 v247, v60, v64
	v_cvt_pk_bf16_f32 v248, v37, v41
	v_cvt_pk_bf16_f32 v249, v45, v49
	v_cvt_pk_bf16_f32 v250, v53, v57
	v_cvt_pk_bf16_f32 v251, v61, v65
	global_store_dwordx4 v[92:93], v[244:247], off
	v_lshl_add_u64 v[230:231], v[92:93], 0, s[68:69]
	global_store_dwordx4 v[230:231], v[248:251], off
	s_nop 1
	v_cvt_pk_bf16_f32 v244, v38, v42
	v_cvt_pk_bf16_f32 v245, v46, v50
	v_cvt_pk_bf16_f32 v246, v54, v58
	v_cvt_pk_bf16_f32 v247, v62, v66
	v_cvt_pk_bf16_f32 v248, v39, v43
	v_cvt_pk_bf16_f32 v249, v47, v51
	v_cvt_pk_bf16_f32 v250, v55, v59
	v_cvt_pk_bf16_f32 v251, v63, v67
	v_lshl_add_u64 v[230:231], v[92:93], 0, s[70:71]
	global_store_dwordx4 v[230:231], v[244:247], off
	v_lshl_add_u64 v[230:231], v[92:93], 0, s[72:73]
	global_store_dwordx4 v[230:231], v[248:251], off
	v_lshl_add_u64 v[92:93], v[92:93], 0, s[74:75]
	v_mov_b64_e32 v[2:3], v[240:241]
	global_load_dwordx4 v[36:39], v[2:3], off offset:896 nt
	v_lshl_add_u64 v[2:3], v[2:3], 0, s[66:67]
	global_load_dwordx4 v[40:43], v[2:3], off offset:896 nt
	v_lshl_add_u64 v[2:3], v[2:3], 0, s[66:67]
	global_load_dwordx4 v[44:47], v[2:3], off offset:896 nt
	v_lshl_add_u64 v[2:3], v[2:3], 0, s[66:67]
	global_load_dwordx4 v[48:51], v[2:3], off offset:896 nt
	v_lshl_add_u64 v[2:3], v[2:3], 0, s[66:67]
	global_load_dwordx4 v[52:55], v[2:3], off offset:896 nt
	v_lshl_add_u64 v[2:3], v[2:3], 0, s[66:67]
	global_load_dwordx4 v[56:59], v[2:3], off offset:896 nt
	v_lshl_add_u64 v[2:3], v[2:3], 0, s[66:67]
	global_load_dwordx4 v[60:63], v[2:3], off offset:896 nt
	v_lshl_add_u64 v[2:3], v[2:3], 0, s[66:67]
	global_load_dwordx4 v[64:67], v[2:3], off offset:896 nt
	s_waitcnt vmcnt(24)
	v_cvt_pk_bf16_f32 v244, v68, v72
	v_cvt_pk_bf16_f32 v245, v76, v80
	v_cvt_pk_bf16_f32 v246, v84, v88
	v_cvt_pk_bf16_f32 v247, v232, v236
	v_cvt_pk_bf16_f32 v248, v69, v73
	v_cvt_pk_bf16_f32 v249, v77, v81
	v_cvt_pk_bf16_f32 v250, v85, v89
	v_cvt_pk_bf16_f32 v251, v233, v237
	global_store_dwordx4 v[92:93], v[244:247], off
	v_lshl_add_u64 v[230:231], v[92:93], 0, s[68:69]
	global_store_dwordx4 v[230:231], v[248:251], off
	s_nop 1
	v_cvt_pk_bf16_f32 v244, v70, v74
	v_cvt_pk_bf16_f32 v245, v78, v82
	v_cvt_pk_bf16_f32 v246, v86, v90
	v_cvt_pk_bf16_f32 v247, v234, v238
	v_cvt_pk_bf16_f32 v248, v71, v75
	v_cvt_pk_bf16_f32 v249, v79, v83
	v_cvt_pk_bf16_f32 v250, v87, v91
	v_cvt_pk_bf16_f32 v251, v235, v239
	v_lshl_add_u64 v[230:231], v[92:93], 0, s[70:71]
	global_store_dwordx4 v[230:231], v[244:247], off
	v_lshl_add_u64 v[230:231], v[92:93], 0, s[72:73]
	global_store_dwordx4 v[230:231], v[248:251], off
	v_lshl_add_u64 v[92:93], v[92:93], 0, s[74:75]
	s_waitcnt vmcnt(16)
	v_cvt_pk_bf16_f32 v244, v4, v8
	v_cvt_pk_bf16_f32 v245, v12, v16
	v_cvt_pk_bf16_f32 v246, v20, v24
	v_cvt_pk_bf16_f32 v247, v28, v32
	v_cvt_pk_bf16_f32 v248, v5, v9
	v_cvt_pk_bf16_f32 v249, v13, v17
	v_cvt_pk_bf16_f32 v250, v21, v25
	v_cvt_pk_bf16_f32 v251, v29, v33
	global_store_dwordx4 v[92:93], v[244:247], off
	v_lshl_add_u64 v[230:231], v[92:93], 0, s[68:69]
	global_store_dwordx4 v[230:231], v[248:251], off
	s_nop 1
	v_cvt_pk_bf16_f32 v244, v6, v10
	v_cvt_pk_bf16_f32 v245, v14, v18
	v_cvt_pk_bf16_f32 v246, v22, v26
	v_cvt_pk_bf16_f32 v247, v30, v34
	v_cvt_pk_bf16_f32 v248, v7, v11
	v_cvt_pk_bf16_f32 v249, v15, v19
	v_cvt_pk_bf16_f32 v250, v23, v27
	v_cvt_pk_bf16_f32 v251, v31, v35
	v_lshl_add_u64 v[230:231], v[92:93], 0, s[70:71]
	global_store_dwordx4 v[230:231], v[244:247], off
	v_lshl_add_u64 v[230:231], v[92:93], 0, s[72:73]
	global_store_dwordx4 v[230:231], v[248:251], off
	v_lshl_add_u64 v[92:93], v[92:93], 0, s[74:75]
	s_waitcnt vmcnt(8)
	v_cvt_pk_bf16_f32 v244, v36, v40
	v_cvt_pk_bf16_f32 v245, v44, v48
	v_cvt_pk_bf16_f32 v246, v52, v56
	v_cvt_pk_bf16_f32 v247, v60, v64
	v_cvt_pk_bf16_f32 v248, v37, v41
	v_cvt_pk_bf16_f32 v249, v45, v49
	v_cvt_pk_bf16_f32 v250, v53, v57
	v_cvt_pk_bf16_f32 v251, v61, v65
	global_store_dwordx4 v[92:93], v[244:247], off
	v_lshl_add_u64 v[230:231], v[92:93], 0, s[68:69]
	global_store_dwordx4 v[230:231], v[248:251], off
	s_nop 1
	v_cvt_pk_bf16_f32 v244, v38, v42
	v_cvt_pk_bf16_f32 v245, v46, v50
	v_cvt_pk_bf16_f32 v246, v54, v58
	v_cvt_pk_bf16_f32 v247, v62, v66
	v_cvt_pk_bf16_f32 v248, v39, v43
	v_cvt_pk_bf16_f32 v249, v47, v51
	v_cvt_pk_bf16_f32 v250, v55, v59
	v_cvt_pk_bf16_f32 v251, v63, v67
	v_lshl_add_u64 v[230:231], v[92:93], 0, s[70:71]
	global_store_dwordx4 v[230:231], v[244:247], off
	v_lshl_add_u64 v[230:231], v[92:93], 0, s[72:73]
	global_store_dwordx4 v[230:231], v[248:251], off
	v_lshl_add_u64 v[92:93], v[92:93], 0, s[74:75]
	s_branch .LBB0_1059

	.amdhsa_kernel _Z10fwd_kernel4Args
		.amdhsa_group_segment_fixed_size 0
		.amdhsa_private_segment_fixed_size 0
		.amdhsa_kernarg_size 576
		.amdhsa_user_sgpr_count 2
		.amdhsa_user_sgpr_dispatch_ptr 0
		.amdhsa_user_sgpr_queue_ptr 0
		.amdhsa_user_sgpr_kernarg_segment_ptr 1
		.amdhsa_user_sgpr_dispatch_id 0
		.amdhsa_user_sgpr_kernarg_preload_length 0
		.amdhsa_user_sgpr_kernarg_preload_offset 0
		.amdhsa_user_sgpr_private_segment_size 0
		.amdhsa_uses_dynamic_stack 0
		.amdhsa_enable_private_segment 0
		.amdhsa_system_sgpr_workgroup_id_x 1
		.amdhsa_system_sgpr_workgroup_id_y 0
		.amdhsa_system_sgpr_workgroup_id_z 0
		.amdhsa_system_sgpr_workgroup_info 0
		.amdhsa_system_vgpr_workitem_id 0
		.amdhsa_next_free_vgpr 256
		.amdhsa_next_free_sgpr 102
		.amdhsa_accum_offset 256
		.amdhsa_reserve_vcc 1
		.amdhsa_float_round_mode_32 0
		.amdhsa_float_round_mode_16_64 0
		.amdhsa_float_denorm_mode_32 3
		.amdhsa_float_denorm_mode_16_64 3
		.amdhsa_dx10_clamp 1
		.amdhsa_ieee_mode 1
		.amdhsa_fp16_overflow 0
		.amdhsa_tg_split 0
		.amdhsa_exception_fp_ieee_invalid_op 0
		.amdhsa_exception_fp_denorm_src 0
		.amdhsa_exception_fp_ieee_div_zero 0
		.amdhsa_exception_fp_ieee_overflow 0
		.amdhsa_exception_fp_ieee_underflow 0
		.amdhsa_exception_fp_ieee_inexact 0
		.amdhsa_exception_int_div_zero 0
	.end_amdhsa_kernel

amdhsa.kernels:
  - .agpr_count:     0
    .args:
      - .offset:         0
        .size:           320
        .value_kind:     by_value
      - .offset:         320
        .size:           4
        .value_kind:     hidden_block_count_x
      - .offset:         324
        .size:           4
        .value_kind:     hidden_block_count_y
      - .offset:         328
        .size:           4
        .value_kind:     hidden_block_count_z
      - .offset:         332
        .size:           2
        .value_kind:     hidden_group_size_x
      - .offset:         334
        .size:           2
        .value_kind:     hidden_group_size_y
      - .offset:         336
        .size:           2
        .value_kind:     hidden_group_size_z
      - .offset:         338
        .size:           2
        .value_kind:     hidden_remainder_x
      - .offset:         340
        .size:           2
        .value_kind:     hidden_remainder_y
      - .offset:         342
        .size:           2
        .value_kind:     hidden_remainder_z
      - .offset:         360
        .size:           8
        .value_kind:     hidden_global_offset_x
      - .offset:         368
        .size:           8
        .value_kind:     hidden_global_offset_y
      - .offset:         376
        .size:           8
        .value_kind:     hidden_global_offset_z
      - .offset:         384
        .size:           2
        .value_kind:     hidden_grid_dims
      - .offset:         440
        .size:           4
        .value_kind:     hidden_dynamic_lds_size
    .group_segment_fixed_size: 0
    .kernarg_segment_align: 8
    .kernarg_segment_size: 576
    .language:       OpenCL C
    .language_version:
      - 2
      - 0
    .max_flat_workgroup_size: 512
    .name:           _Z10fwd_kernel4Args
    .private_segment_fixed_size: 0
    .sgpr_count:     108
    .sgpr_spill_count: 15
    .symbol:         _Z10fwd_kernel4Args.kd
    .uniform_work_group_size: 1
    .uses_dynamic_stack: false
    .vgpr_count:     256
    .vgpr_spill_count: 0
    .wavefront_size: 64
